# speedup vs baseline: 1.0962x; 1.0187x over previous
; DI int crow(int reg, int h) { return (reg & 3) + 8 * (reg >> 2) + 4 * h; }
; template <int MASK>
; __global__ void __launch_bounds__(256, 2) fwd_megakernel_t(Params p) {
;     ...
;           float rv[16];
; #pragma unroll
;           for (int r = 0; r < 16; r++) rv[r] = rinvx[m0 + wm * 64 + i * 32 + crow(r, hh)];
;     ...
;             } else {
;               const int hd = (n0 - C_DV) >> 7, d = n & 127;
;               const int sh = (hd >> 1) * 2;
;               u16* dst = dvT + ((size_t)(b * 6 + hd) * 128 + d) * S_;
; #pragma unroll
;               for (int r = 0; r < 16; r++) {
;                 const int s = (m0 - b * S_) + wm * 64 + i * 32 + crow(r, hh);
;                 const int pos = ((s & ((1 << sh) - 1)) << (13 - sh)) + (s >> sh);
;                 dst[pos] = f2bf(acc[i][j][r] * rv[r]);
;               }
;             }
.Lp1_dvt:
	v_add_u32_e32 v64, s10, v137
	v_ashrrev_i32_e32 v65, 31, v64
	v_lshl_add_u64 v[66:67], v[64:65], 2, s[80:81]
	global_load_dwordx4 v[68:71], v[66:67], off
	global_load_dwordx4 v[72:75], v[66:67], off offset:32
	global_load_dwordx4 v[76:79], v[66:67], off offset:64
	global_load_dwordx4 v[80:83], v[66:67], off offset:96
	global_load_dwordx4 v[84:87], v[66:67], off offset:128
	global_load_dwordx4 v[88:91], v[66:67], off offset:160
	global_load_dwordx4 v[92:95], v[66:67], off offset:192
	global_load_dwordx4 v[96:99], v[66:67], off offset:224
	v_and_b32_e32 v100, 31, v152
	v_bfe_u32 v101, v152, 5, 1
	v_bfe_u32 v102, v152, 6, 1
	v_lshrrev_b32_e32 v103, 7, v152
	v_lshl_add_u32 v104, v102, 6, v100
	v_mul_u32_u24_e32 v104, 0x104, v104
	v_lshlrev_b32_e32 v105, 7, v103
	v_lshl_add_u32 v105, v101, 3, v105
	v_add_u32_e32 v104, v104, v105
	s_waitcnt vmcnt(0)
	v_mul_f32_e32 v48, v48, v68
	v_mul_f32_e32 v49, v49, v69
	v_cvt_pk_bf16_f32 v48, v48, v49
	ds_write_b32 v104, v48
	v_mul_f32_e32 v50, v50, v70
	v_mul_f32_e32 v51, v51, v71
	v_cvt_pk_bf16_f32 v50, v50, v51
	ds_write_b32 v104, v50 offset:4
	v_mul_f32_e32 v52, v52, v72
	v_mul_f32_e32 v53, v53, v73
	v_cvt_pk_bf16_f32 v52, v52, v53
	ds_write_b32 v104, v52 offset:16
	v_mul_f32_e32 v54, v54, v74
	v_mul_f32_e32 v55, v55, v75
	v_cvt_pk_bf16_f32 v54, v54, v55
	ds_write_b32 v104, v54 offset:20
	v_mul_f32_e32 v56, v56, v76
	v_mul_f32_e32 v57, v57, v77
	v_cvt_pk_bf16_f32 v56, v56, v57
	ds_write_b32 v104, v56 offset:32
	v_mul_f32_e32 v58, v58, v78
	v_mul_f32_e32 v59, v59, v79
	v_cvt_pk_bf16_f32 v58, v58, v59
	ds_write_b32 v104, v58 offset:36
	v_mul_f32_e32 v60, v60, v80
	v_mul_f32_e32 v61, v61, v81
	v_cvt_pk_bf16_f32 v60, v60, v61
	ds_write_b32 v104, v60 offset:48
	v_mul_f32_e32 v62, v62, v82
	v_mul_f32_e32 v63, v63, v83
	v_cvt_pk_bf16_f32 v62, v62, v63
	ds_write_b32 v104, v62 offset:52
	v_mul_f32_e32 v32, v32, v68
	v_mul_f32_e32 v33, v33, v69
	v_cvt_pk_bf16_f32 v32, v32, v33
	ds_write_b32 v104, v32 offset:8320
	v_mul_f32_e32 v34, v34, v70
	v_mul_f32_e32 v35, v35, v71
	v_cvt_pk_bf16_f32 v34, v34, v35
	ds_write_b32 v104, v34 offset:8324
	v_mul_f32_e32 v36, v36, v72
	v_mul_f32_e32 v37, v37, v73
	v_cvt_pk_bf16_f32 v36, v36, v37
	ds_write_b32 v104, v36 offset:8336
	v_mul_f32_e32 v38, v38, v74
	v_mul_f32_e32 v39, v39, v75
	v_cvt_pk_bf16_f32 v38, v38, v39
	ds_write_b32 v104, v38 offset:8340
	v_mul_f32_e32 v40, v40, v76
	v_mul_f32_e32 v41, v41, v77
	v_cvt_pk_bf16_f32 v40, v40, v41
	ds_write_b32 v104, v40 offset:8352
	v_mul_f32_e32 v42, v42, v78
	v_mul_f32_e32 v43, v43, v79
	v_cvt_pk_bf16_f32 v42, v42, v43
	ds_write_b32 v104, v42 offset:8356
	v_mul_f32_e32 v44, v44, v80
	v_mul_f32_e32 v45, v45, v81
	v_cvt_pk_bf16_f32 v44, v44, v45
	ds_write_b32 v104, v44 offset:8368
	v_mul_f32_e32 v46, v46, v82
	v_mul_f32_e32 v47, v47, v83
	v_cvt_pk_bf16_f32 v46, v46, v47
	ds_write_b32 v104, v46 offset:8372
	v_mul_f32_e32 v16, v16, v84
	v_mul_f32_e32 v17, v17, v85
	v_cvt_pk_bf16_f32 v16, v16, v17
	ds_write_b32 v104, v16 offset:64
	v_mul_f32_e32 v18, v18, v86
	v_mul_f32_e32 v19, v19, v87
	v_cvt_pk_bf16_f32 v18, v18, v19
	ds_write_b32 v104, v18 offset:68
	v_mul_f32_e32 v20, v20, v88
	v_mul_f32_e32 v21, v21, v89
	v_cvt_pk_bf16_f32 v20, v20, v21
	ds_write_b32 v104, v20 offset:80
	v_mul_f32_e32 v22, v22, v90
	v_mul_f32_e32 v23, v23, v91
	v_cvt_pk_bf16_f32 v22, v22, v23
	ds_write_b32 v104, v22 offset:84
	v_mul_f32_e32 v24, v24, v92
	v_mul_f32_e32 v25, v25, v93
	v_cvt_pk_bf16_f32 v24, v24, v25
	ds_write_b32 v104, v24 offset:96
	v_mul_f32_e32 v26, v26, v94
	v_mul_f32_e32 v27, v27, v95
	v_cvt_pk_bf16_f32 v26, v26, v27
	ds_write_b32 v104, v26 offset:100
	v_mul_f32_e32 v28, v28, v96
	v_mul_f32_e32 v29, v29, v97
	v_cvt_pk_bf16_f32 v28, v28, v29
	ds_write_b32 v104, v28 offset:112
	v_mul_f32_e32 v30, v30, v98
	v_mul_f32_e32 v31, v31, v99
	v_cvt_pk_bf16_f32 v30, v30, v31
	ds_write_b32 v104, v30 offset:116
	v_mul_f32_e32 v0, v0, v84
	v_mul_f32_e32 v1, v1, v85
	v_cvt_pk_bf16_f32 v0, v0, v1
	ds_write_b32 v104, v0 offset:8384
	v_mul_f32_e32 v2, v2, v86
	v_mul_f32_e32 v3, v3, v87
	v_cvt_pk_bf16_f32 v2, v2, v3
	ds_write_b32 v104, v2 offset:8388
	v_mul_f32_e32 v4, v4, v88
	v_mul_f32_e32 v5, v5, v89
	v_cvt_pk_bf16_f32 v4, v4, v5
	ds_write_b32 v104, v4 offset:8400
	v_mul_f32_e32 v6, v6, v90
	v_mul_f32_e32 v7, v7, v91
	v_cvt_pk_bf16_f32 v6, v6, v7
	ds_write_b32 v104, v6 offset:8404
	v_mul_f32_e32 v8, v8, v92
	v_mul_f32_e32 v9, v9, v93
	v_cvt_pk_bf16_f32 v8, v8, v9
	ds_write_b32 v104, v8 offset:8416
	v_mul_f32_e32 v10, v10, v94
	v_mul_f32_e32 v11, v11, v95
	v_cvt_pk_bf16_f32 v10, v10, v11
	ds_write_b32 v104, v10 offset:8420
	v_mul_f32_e32 v12, v12, v96
	v_mul_f32_e32 v13, v13, v97
	v_cvt_pk_bf16_f32 v12, v12, v13
	ds_write_b32 v104, v12 offset:8432
	v_mul_f32_e32 v14, v14, v98
	v_mul_f32_e32 v15, v15, v99
	v_cvt_pk_bf16_f32 v14, v14, v15
	ds_write_b32 v104, v14 offset:8436
	s_waitcnt lgkmcnt(0)
	s_barrier
; DI int crow(int reg, int h) { return (reg & 3) + 8 * (reg >> 2) + 4 * h; }
; template <int MASK>
; __global__ void __launch_bounds__(256, 2) fwd_megakernel_t(Params p) {
;     ...
;             } else {
;               const int hd = (n0 - C_DV) >> 7, d = n & 127;
;               const int sh = (hd >> 1) * 2;
;               u16* dst = dvT + ((size_t)(b * 6 + hd) * 128 + d) * S_;
; #pragma unroll
;               for (int r = 0; r < 16; r++) {
;                 const int s = (m0 - b * S_) + wm * 64 + i * 32 + crow(r, hh);
;                 const int pos = ((s & ((1 << sh) - 1)) << (13 - sh)) + (s >> sh);
;                 dst[pos] = f2bf(acc[i][j][r] * rv[r]);
;               }
;             }
	s_sub_i32 s38, s25, 24
	s_lshr_b32 s39, s38, 1
	s_lshl_b32 s39, s39, 1
	s_lshr_b32 s46, s24, 6
	s_mul_i32 s46, s46, 6
	s_add_i32 s46, s46, s38
	s_lshl_b32 s48, s46, 21
	s_lshr_b32 s49, s46, 11
	s_add_u32 s30, s73, s48
	s_addc_u32 s31, s26, s49
	s_and_b32 s48, s24, 63
	s_lshl_b32 s48, s48, 7
	s_lshr_b32 s48, s48, s39
	s_sub_i32 s49, 7, s39
	s_sub_i32 s50, 13, s39
	s_lshr_b32 s46, 0x80, s39
	s_add_i32 s46, s46, -1
	v_and_b32_e32 v100, 63, v152
	v_lshlrev_b32_e32 v100, 1, v100
	v_lshrrev_b32_e32 v101, s49, v100
	v_and_b32_e32 v102, s46, v100
	v_lshlrev_b32_e32 v105, s39, v102
	v_add_u32_e32 v105, v105, v101
	v_lshlrev_b32_e32 v105, 1, v105
	v_lshrrev_b32_e32 v106, 6, v152
	v_mul_u32_u24_e32 v107, 0x2080, v106
	v_add_u32_e32 v105, v105, v107
	s_lshl_b32 s46, 2, s39
	v_add_u32_e32 v108, s46, v105
	v_lshlrev_b32_e32 v109, s50, v101
	v_add3_u32 v109, v109, v102, s48
	v_lshlrev_b32_e32 v109, 1, v109
	s_nop 0
	v_readfirstlane_b32 s46, v106
	s_lshl_b32 s46, s46, 19
	s_add_u32 s30, s30, s46
	s_addc_u32 s31, s31, 0
	ds_read_u16 v110, v105
	ds_read_u16 v118, v108
	ds_read_u16 v111, v105 offset:260
	ds_read_u16 v119, v108 offset:260
	ds_read_u16 v112, v105 offset:520
	ds_read_u16 v120, v108 offset:520
	ds_read_u16 v113, v105 offset:780
	ds_read_u16 v121, v108 offset:780
	ds_read_u16 v114, v105 offset:1040
	ds_read_u16 v122, v108 offset:1040
	ds_read_u16 v115, v105 offset:1300
	ds_read_u16 v123, v108 offset:1300
	ds_read_u16 v116, v105 offset:1560
	ds_read_u16 v124, v108 offset:1560
	ds_read_u16 v117, v105 offset:1820
	ds_read_u16 v125, v108 offset:1820
	s_waitcnt lgkmcnt(0)
	v_lshl_or_b32 v110, v118, 16, v110
	v_lshl_or_b32 v111, v119, 16, v111
	v_lshl_or_b32 v112, v120, 16, v112
	v_lshl_or_b32 v113, v121, 16, v113
	v_lshl_or_b32 v114, v122, 16, v114
	v_lshl_or_b32 v115, v123, 16, v115
	v_lshl_or_b32 v116, v124, 16, v116
	v_lshl_or_b32 v117, v125, 16, v117
	s_add_u32 s34, s30, 0x0
	s_addc_u32 s35, s31, 0
	global_store_dword v109, v110, s[34:35]
	s_add_u32 s34, s30, 0x4000
	s_addc_u32 s35, s31, 0
	global_store_dword v109, v111, s[34:35]
	s_add_u32 s34, s30, 0x8000
	s_addc_u32 s35, s31, 0
	global_store_dword v109, v112, s[34:35]
	s_add_u32 s34, s30, 0xc000
	s_addc_u32 s35, s31, 0
	global_store_dword v109, v113, s[34:35]
	s_add_u32 s34, s30, 0x10000
	s_addc_u32 s35, s31, 0
	global_store_dword v109, v114, s[34:35]
	s_add_u32 s34, s30, 0x14000
	s_addc_u32 s35, s31, 0
	global_store_dword v109, v115, s[34:35]
	s_add_u32 s34, s30, 0x18000
	s_addc_u32 s35, s31, 0
	global_store_dword v109, v116, s[34:35]
	s_add_u32 s34, s30, 0x1c000
	s_addc_u32 s35, s31, 0
	global_store_dword v109, v117, s[34:35]
	ds_read_u16 v110, v105 offset:2080
	ds_read_u16 v118, v108 offset:2080
	ds_read_u16 v111, v105 offset:2340
	ds_read_u16 v119, v108 offset:2340
	ds_read_u16 v112, v105 offset:2600
	ds_read_u16 v120, v108 offset:2600
	ds_read_u16 v113, v105 offset:2860
	ds_read_u16 v121, v108 offset:2860
	ds_read_u16 v114, v105 offset:3120
	ds_read_u16 v122, v108 offset:3120
	ds_read_u16 v115, v105 offset:3380
	ds_read_u16 v123, v108 offset:3380
	ds_read_u16 v116, v105 offset:3640
	ds_read_u16 v124, v108 offset:3640
	ds_read_u16 v117, v105 offset:3900
	ds_read_u16 v125, v108 offset:3900
	s_waitcnt lgkmcnt(0)
; DI int crow(int reg, int h) { return (reg & 3) + 8 * (reg >> 2) + 4 * h; }
; template <int MASK>
; __global__ void __launch_bounds__(256, 2) fwd_megakernel_t(Params p) {
;     ...
;             } else {
;               const int hd = (n0 - C_DV) >> 7, d = n & 127;
;               const int sh = (hd >> 1) * 2;
;               u16* dst = dvT + ((size_t)(b * 6 + hd) * 128 + d) * S_;
; #pragma unroll
;               for (int r = 0; r < 16; r++) {
;                 const int s = (m0 - b * S_) + wm * 64 + i * 32 + crow(r, hh);
;                 const int pos = ((s & ((1 << sh) - 1)) << (13 - sh)) + (s >> sh);
;                 dst[pos] = f2bf(acc[i][j][r] * rv[r]);
;               }
;             }
	v_lshl_or_b32 v110, v118, 16, v110
	v_lshl_or_b32 v111, v119, 16, v111
	v_lshl_or_b32 v112, v120, 16, v112
	v_lshl_or_b32 v113, v121, 16, v113
	v_lshl_or_b32 v114, v122, 16, v114
	v_lshl_or_b32 v115, v123, 16, v115
	v_lshl_or_b32 v116, v124, 16, v116
	v_lshl_or_b32 v117, v125, 16, v117
	s_add_u32 s34, s30, 0x20000
	s_addc_u32 s35, s31, 0
	global_store_dword v109, v110, s[34:35]
	s_add_u32 s34, s30, 0x24000
	s_addc_u32 s35, s31, 0
	global_store_dword v109, v111, s[34:35]
	s_add_u32 s34, s30, 0x28000
	s_addc_u32 s35, s31, 0
	global_store_dword v109, v112, s[34:35]
	s_add_u32 s34, s30, 0x2c000
	s_addc_u32 s35, s31, 0
	global_store_dword v109, v113, s[34:35]
	s_add_u32 s34, s30, 0x30000
	s_addc_u32 s35, s31, 0
	global_store_dword v109, v114, s[34:35]
	s_add_u32 s34, s30, 0x34000
	s_addc_u32 s35, s31, 0
	global_store_dword v109, v115, s[34:35]
	s_add_u32 s34, s30, 0x38000
	s_addc_u32 s35, s31, 0
	global_store_dword v109, v116, s[34:35]
	s_add_u32 s34, s30, 0x3c000
	s_addc_u32 s35, s31, 0
	global_store_dword v109, v117, s[34:35]
	ds_read_u16 v110, v105 offset:4160
	ds_read_u16 v118, v108 offset:4160
	ds_read_u16 v111, v105 offset:4420
	ds_read_u16 v119, v108 offset:4420
	ds_read_u16 v112, v105 offset:4680
	ds_read_u16 v120, v108 offset:4680
	ds_read_u16 v113, v105 offset:4940
	ds_read_u16 v121, v108 offset:4940
	ds_read_u16 v114, v105 offset:5200
	ds_read_u16 v122, v108 offset:5200
	ds_read_u16 v115, v105 offset:5460
	ds_read_u16 v123, v108 offset:5460
	ds_read_u16 v116, v105 offset:5720
	ds_read_u16 v124, v108 offset:5720
	ds_read_u16 v117, v105 offset:5980
	ds_read_u16 v125, v108 offset:5980
	s_waitcnt lgkmcnt(0)
	v_lshl_or_b32 v110, v118, 16, v110
	v_lshl_or_b32 v111, v119, 16, v111
	v_lshl_or_b32 v112, v120, 16, v112
	v_lshl_or_b32 v113, v121, 16, v113
	v_lshl_or_b32 v114, v122, 16, v114
	v_lshl_or_b32 v115, v123, 16, v115
	v_lshl_or_b32 v116, v124, 16, v116
	v_lshl_or_b32 v117, v125, 16, v117
	s_add_u32 s34, s30, 0x40000
	s_addc_u32 s35, s31, 0
	global_store_dword v109, v110, s[34:35]
	s_add_u32 s34, s30, 0x44000
	s_addc_u32 s35, s31, 0
	global_store_dword v109, v111, s[34:35]
	s_add_u32 s34, s30, 0x48000
	s_addc_u32 s35, s31, 0
	global_store_dword v109, v112, s[34:35]
	s_add_u32 s34, s30, 0x4c000
	s_addc_u32 s35, s31, 0
	global_store_dword v109, v113, s[34:35]
	s_add_u32 s34, s30, 0x50000
	s_addc_u32 s35, s31, 0
	global_store_dword v109, v114, s[34:35]
	s_add_u32 s34, s30, 0x54000
	s_addc_u32 s35, s31, 0
	global_store_dword v109, v115, s[34:35]
	s_add_u32 s34, s30, 0x58000
	s_addc_u32 s35, s31, 0
	global_store_dword v109, v116, s[34:35]
	s_add_u32 s34, s30, 0x5c000
	s_addc_u32 s35, s31, 0
	global_store_dword v109, v117, s[34:35]
	ds_read_u16 v110, v105 offset:6240
	ds_read_u16 v118, v108 offset:6240
	ds_read_u16 v111, v105 offset:6500
	ds_read_u16 v119, v108 offset:6500
	ds_read_u16 v112, v105 offset:6760
	ds_read_u16 v120, v108 offset:6760
	ds_read_u16 v113, v105 offset:7020
	ds_read_u16 v121, v108 offset:7020
	ds_read_u16 v114, v105 offset:7280
	ds_read_u16 v122, v108 offset:7280
	ds_read_u16 v115, v105 offset:7540
	ds_read_u16 v123, v108 offset:7540
	ds_read_u16 v116, v105 offset:7800
	ds_read_u16 v124, v108 offset:7800
	ds_read_u16 v117, v105 offset:8060
	ds_read_u16 v125, v108 offset:8060
	s_waitcnt lgkmcnt(0)
	v_lshl_or_b32 v110, v118, 16, v110
	v_lshl_or_b32 v111, v119, 16, v111
	v_lshl_or_b32 v112, v120, 16, v112
	v_lshl_or_b32 v113, v121, 16, v113
	v_lshl_or_b32 v114, v122, 16, v114
	v_lshl_or_b32 v115, v123, 16, v115
	v_lshl_or_b32 v116, v124, 16, v116
	v_lshl_or_b32 v117, v125, 16, v117
	s_add_u32 s34, s30, 0x60000
	s_addc_u32 s35, s31, 0
	global_store_dword v109, v110, s[34:35]
	s_add_u32 s34, s30, 0x64000
	s_addc_u32 s35, s31, 0
	global_store_dword v109, v111, s[34:35]
	s_add_u32 s34, s30, 0x68000
	s_addc_u32 s35, s31, 0
	global_store_dword v109, v112, s[34:35]
	s_add_u32 s34, s30, 0x6c000
	s_addc_u32 s35, s31, 0
	global_store_dword v109, v113, s[34:35]
	s_add_u32 s34, s30, 0x70000
	s_addc_u32 s35, s31, 0
	global_store_dword v109, v114, s[34:35]
	s_add_u32 s34, s30, 0x74000
	s_addc_u32 s35, s31, 0
	global_store_dword v109, v115, s[34:35]
	s_add_u32 s34, s30, 0x78000
	s_addc_u32 s35, s31, 0
	global_store_dword v109, v116, s[34:35]
	s_add_u32 s34, s30, 0x7c000
	s_addc_u32 s35, s31, 0
	global_store_dword v109, v117, s[34:35]
	s_branch .LBB0_771
.LBB0_740:
	s_cmp_lt_i32 s25, 24
	s_cbranch_scc1 .Lp1_nodvt
	s_cmp_lt_i32 s25, 30
	s_cbranch_scc1 .Lp1_dvt
